# v31 + GEMM main loop: per-MMA-block s_setprio toggles removed, one static priority raise for the wave half that arrives second (wr==1), reset at phase exit
# baseline (speedup 1.0000x reference)
; #define PG8_STAGE(bufoff, gbase, voff) do { _Pragma("unroll") for (int _i = 0; _i < 2; ++_i) \
;     __builtin_amdgcn_global_load_lds((const unsigned*)((const char*)(gbase) + (voff)[_i]), (LAS unsigned*)(lds + (bufoff) + ldsw + _i * 8192), 16, 0, 0); } while (0)
; #define PG8_WAIT_V(n) asm volatile("s_waitcnt vmcnt(" #n ")" ::: "memory")
; template <class Epi>
; __device__ __forceinline__ void gemm_phase(LAS unsigned char* lds, const Gemm g, const Epi& E) {
;   int tid_ = threadIdx.x; asm volatile("" : "+v"(tid_));
;   const int tid = tid_, wid = __builtin_amdgcn_readfirstlane(tid >> 6), lane = tid & 63, wr = wid >> 2, wc = wid & 3, fr = lane & 15, fq = lane >> 4;
;   const int K = g.K, nt = K / BK;
;   StaticOrder S; S.init(g.M, g.N, gridDim.x, g.rev ? (int)gridDim.x - 1 - (int)blockIdx.x : (int)blockIdx.x, g.A2 != nullptr);
;   unsigned voffA[2], voffB[2];
; #pragma unroll
;   for (int i = 0; i < 2; ++i) { int R, C; stage_rc(tid * 16 + i * 8192, R, C); const int Rb = (R & ~31) + perm32(R & 31);
;     voffA[i] = (unsigned)(R * g.lda + C) * 2u; voffB[i] = (unsigned)(Rb * g.ldb + C) * 2u; }
;   const size_t kstep = (size_t)(BK * 2);
;   const size_t hstepA = (size_t)HALF * g.lda * 2, hstepB = (size_t)HALF * g.ldb * 2;
;   const size_t tstepA = 2 * hstepA, tstepB = 2 * hstepB;
;   const unsigned ldsw = (unsigned)wid * 1024u;
;   const int aoff = lds_byte(wr * 64 + fr, fq * 8), boff = lds_byte(wc * 32 + fr, fq * 8);
;     ...
;   Unit cur, nxt; int ui = 0;
;   if (!S.next(0, cur)) return;
;   f32x4 acc[2][2][4][2];
; #pragma unroll
;   for (int a = 0; a < 2; ++a)
; #pragma unroll
;     for (int b = 0; b < 2; ++b)
; #pragma unroll
;       for (int m = 0; m < 4; ++m)
; #pragma unroll
;         for (int n = 0; n < 2; ++n) acc[a][b][m][n] = (f32x4){0.f, 0.f, 0.f, 0.f};
;   bf16x8 At[4][2], B0[2][2], B1[2][2];
;   const char* cA = (const char*)(cur.w ? g.A2 : g.A) + (size_t)cur.pm * tstepA; const char* cB = (const char*)(cur.w ? g.Bt2 : g.Bt) + (size_t)cur.pn * tstepB;
;   PG8_STAGE(PG8_SB(0, 0), cB, voffB); PG8_STAGE(PG8_SA(0, 0), cA, voffA); PG8_STAGE(PG8_SB(0, 1), cB + hstepB, voffB); PG8_STAGE(PG8_SA(0, 1), cA + hstepA, voffA);
;   if (wr == 1) PG8_BAR;
;   PG8_WAIT_V(4); PG8_BAR;
;   PG8_STAGE(PG8_SB(1, 0), cB + kstep, voffB); PG8_STAGE(PG8_SA(1, 0), cA + kstep, voffA); PG8_STAGE(PG8_SB(1, 1), cB + hstepB + kstep, voffB);
;   PG8_WAIT_V(6); PG8_BAR;
.LBB0_563:
	s_andn2_b64 vcc, exec, s[36:37]
	s_cbranch_vccnz .LBB0_1255
	v_bfe_i32 v2, v18, 27, 1
	v_lshlrev_b32_e32 v0, 4, v18
	v_lshrrev_b32_e32 v2, 22, v2
	v_add_u32_e32 v2, v0, v2
	v_and_b32_e32 v2, 0xfffffc00, v2
	v_sub_u32_e32 v2, v0, v2
	v_ashrrev_i32_e32 v1, 31, v18
	v_lshrrev_b32_e32 v3, 4, v2
	v_lshrrev_b32_e32 v1, 26, v1
	v_bitop3_b32 v2, v3, v2, 32 bitop3:0x6c
	v_add_u32_e32 v1, v18, v1
	v_ashrrev_i32_e32 v4, 31, v2
	v_ashrrev_i32_e32 v1, 6, v1
	v_lshrrev_b32_e32 v4, 26, v4
	v_lshlrev_b32_e32 v3, 3, v1
	v_add_u32_e32 v4, v2, v4
	v_and_b32_e32 v3, -16, v3
	v_ashrrev_i32_e32 v5, 6, v4
	v_lshlrev_b32_e32 v1, 5, v1
	v_add_u32_e32 v3, v5, v3
	v_and_b32_e32 v12, 32, v1
	v_and_b32_e32 v1, 0xc0, v4
	v_sub_u32_e32 v1, v2, v1
	v_lshlrev_b32_e32 v2, 1, v3
	v_lshrrev_b32_e32 v4, 2, v3
	v_and_b32_e32 v5, 3, v5
	s_mov_b32 s1, 0x7fffffe0
	v_ashrrev_i16_sdwa v1, v230, sext(v1) dst_sel:DWORD dst_unused:UNUSED_PAD src0_sel:DWORD src1_sel:BYTE_0
	v_and_b32_e32 v2, 24, v2
	v_and_b32_e32 v4, 4, v4
	v_and_or_b32 v5, v3, s1, v5
	v_bfe_i32 v13, v1, 0, 16
	v_or3_b32 v2, v5, v4, v2
	v_add_u32_e32 v1, v12, v13
	v_mul_lo_u32 v14, v3, s20
	v_mul_lo_u32 v2, v2, s29
	v_add_u32_e32 v0, 0x2000, v0
	v_add_lshl_u32 v138, v1, v14, 1
	v_add_lshl_u32 v132, v2, v1, 1
	v_ashrrev_i32_e32 v1, 31, v0
	v_lshrrev_b32_e32 v1, 22, v1
	v_add_u32_e32 v1, v0, v1
	v_ashrrev_i32_e32 v1, 10, v1
	v_mul_i32_i24_e32 v2, 0x400, v1
	v_sub_u32_e32 v0, v0, v2
	v_lshrrev_b32_e32 v2, 4, v0
	v_bitop3_b32 v0, v2, v0, 32 bitop3:0x6c
	s_lshl_b32 s56, s20, 8
	v_ashrrev_i32_e32 v3, 31, v0
	s_lshl_b64 s[30:31], s[56:57], 1
	s_ashr_i32 s2, s75, 31
	v_lshrrev_b32_e32 v3, 26, v3
	s_mul_i32 s2, s30, s2
	s_mul_hi_u32 s3, s30, s75
	v_lshlrev_b32_e32 v2, 3, v1
	v_add_u32_e32 v3, v0, v3
	s_add_i32 s2, s3, s2
	s_bfe_u32 s3, s20, 0x10017
	v_and_b32_e32 v2, -16, v2
	v_ashrrev_i32_e32 v4, 6, v3
	s_mul_i32 s3, s3, s75
	v_add_u32_e32 v2, v4, v2
	s_lshl_b32 s96, s29, 9
	s_add_i32 s3, s2, s3
	s_ashr_i32 s2, s53, 31
	s_ashr_i32 s0, s35, 6
	v_and_b32_e32 v4, 3, v4
	v_mul_lo_u32 v17, v2, s20
	s_mul_i32 s2, s96, s2
	s_mul_hi_u32 s20, s96, s53
	v_and_or_b32 v4, v2, s1, v4
	s_ashr_i32 s1, s35, 8
	s_lshl_b32 s95, s29, 8
	s_lshl_b32 s97, s0, 10
	s_add_i32 s20, s20, s2
	v_lshlrev_b32_e32 v1, 5, v1
	s_cmp_eq_u32 s12, 0
	v_and_b32_e32 v15, 32, v1
	v_and_b32_e32 v1, 0xc0, v3
	s_cselect_b32 s26, s62, s42
	s_mul_i32 s27, s96, s53
	v_sub_u32_e32 v0, v0, v1
	v_lshlrev_b32_e32 v1, 1, v2
	v_lshrrev_b32_e32 v3, 2, v2
	v_writelane_b32 v255, s35, 29
	s_cselect_b32 s21, s63, s43
	s_cselect_b32 s35, s61, s71
	s_cselect_b32 s36, s60, s70
	s_add_u32 s26, s26, s27
	v_ashrrev_i16_sdwa v0, v230, sext(v0) dst_sel:DWORD dst_unused:UNUSED_PAD src0_sel:DWORD src1_sel:BYTE_0
	v_and_b32_e32 v1, 24, v1
	v_and_b32_e32 v3, 4, v3
	s_addc_u32 s27, s21, s20
	s_add_i32 s84, s97, 0
	v_bfe_i32 v16, v0, 0, 16
	v_or3_b32 v1, v4, v3, v1
	s_add_i32 m0, s84, 0x10000
	v_add_u32_e32 v0, v15, v16
	v_mul_lo_u32 v1, v1, s29
	s_mul_i32 s2, s30, s75
	global_load_lds_dwordx4 v132, s[26:27]
	s_add_i32 m0, s84, 0x12000
	v_add_lshl_u32 v142, v1, v0, 1
	s_add_u32 s2, s36, s2
	global_load_lds_dwordx4 v142, s[26:27]
	s_addc_u32 s3, s35, s3
	s_mov_b32 m0, s84
	s_add_i32 s85, s84, 0x2000
	v_add_lshl_u32 v140, v0, v17, 1
	global_load_lds_dwordx4 v138, s[2:3]
	s_mov_b32 m0, s85
	s_add_u32 s20, s26, s95
	global_load_lds_dwordx4 v140, s[2:3]
	s_addc_u32 s21, s27, 0
	s_add_i32 m0, s84, 0x14000
	v_mov_b32_e32 v143, v133
	global_load_lds_dwordx4 v132, s[20:21]
	s_add_i32 m0, s84, 0x16000
	v_lshl_add_u64 v[8:9], s[20:21], 0, v[132:133]
	v_lshl_add_u64 v[10:11], s[20:21], 0, v[142:143]
	global_load_lds_dwordx4 v142, s[20:21]
	s_add_u32 s20, s2, s56
	s_addc_u32 s21, s3, 0
	s_add_i32 s86, s84, 0x4000
	s_mov_b32 m0, s86
	s_add_i32 s87, s84, 0x6000
	global_load_lds_dwordx4 v138, s[20:21]
	s_mov_b32 m0, s87
	v_mov_b32_e32 v139, v133
	global_load_lds_dwordx4 v140, s[20:21]
	v_mov_b32_e32 v141, v133
	v_lshl_add_u64 v[0:1], s[26:27], 0, v[132:133]
	v_lshl_add_u64 v[2:3], s[26:27], 0, v[142:143]
	v_lshl_add_u64 v[4:5], s[2:3], 0, v[138:139]
	v_lshl_add_u64 v[6:7], s[2:3], 0, v[140:141]
	s_cmp_lg_u32 s1, 1
	s_cbranch_scc1 .LBB0_566
	s_setprio 1
	s_barrier

; #define PG8_STAGE(bufoff, gbase, voff) do { _Pragma("unroll") for (int _i = 0; _i < 2; ++_i) \
;     __builtin_amdgcn_global_load_lds((const unsigned*)((const char*)(gbase) + (voff)[_i]), (LAS unsigned*)(lds + (bufoff) + ldsw + _i * 8192), 16, 0, 0); } while (0)
; #define PG8_LDA(dst, b, h) do { _Pragma("unroll") for (int m = 0; m < 4; ++m) _Pragma("unroll") for (int k = 0; k < 2; ++k) dst[m][k] = *(const LAS bf16x8*)(lds + PG8_SA(b, h) + aoff + m * 2048 + k * 1024); } while (0)
; #define PG8_LDB(dst, b, h) do { _Pragma("unroll") for (int n = 0; n < 2; ++n) _Pragma("unroll") for (int k = 0; k < 2; ++k) dst[n][k] = *(const LAS bf16x8*)(lds + PG8_SB(b, h) + boff + n * 2048 + k * 1024); } while (0)
; #define PG8_MMA(ai, bj, At, Bt) do { __builtin_amdgcn_s_setprio(1); _Pragma("unroll") for (int m = 0; m < 4; ++m) _Pragma("unroll") for (int n = 0; n < 2; ++n) _Pragma("unroll") for (int k = 0; k < 2; ++k) \
;     acc[ai][bj][m][n] = __builtin_amdgcn_mfma_f32_16x16x32_bf16(Bt[n][k], At[m][k], acc[ai][bj][m][n], 0, 0, 0); __builtin_amdgcn_s_setprio(0); } while (0)
; #define PG8_WAIT_V(n) asm volatile("s_waitcnt vmcnt(" #n ")" ::: "memory")
; #define PG8_WAIT_L(n) asm volatile("s_waitcnt lgkmcnt(" #n ")" ::: "memory")
; #define PG8_BAR __builtin_amdgcn_s_barrier()
; #define PG8_SCHED __builtin_amdgcn_sched_barrier(0)
; template <class Epi>
; __device__ __forceinline__ void gemm_phase(LAS unsigned char* lds, const Gemm g, const Epi& E) {
;     ...
;     for (int t = 0; t < nt; t += 2) {
;       const bool last = (t == nt - 2);
;       const char* a1 = cA + (size_t)(t + 1) * kstep;
;       const char* a2 = last ? nA : cA + (size_t)(t + 2) * kstep; const char* b2 = last ? nB : cB + (size_t)(t + 2) * kstep;
;       const char* a3 = a2 + kstep; const char* b3 = b2 + kstep;
;       PG8_LDB(B0, 0, 0); PG8_SCHED; PG8_LDA(At, 0, 0); PG8_STAGE(PG8_SA(1, 1), a1 + hstepA, voffA);
;       PG8_WAIT_L(8); PG8_BAR; PG8_WAIT_L(0); PG8_MMA(0, 0, At, B0); PG8_BAR; PG8_SCHED;
;       PG8_LDB(B1, 0, 1); PG8_STAGE(PG8_SB(0, 0), b2, voffB);
;       PG8_BAR; PG8_WAIT_L(0); PG8_MMA(0, 1, At, B1); PG8_BAR;
;       PG8_LDA(At, 0, 1); PG8_STAGE(PG8_SA(0, 0), a2, voffA);
;       PG8_BAR; PG8_WAIT_L(0); PG8_MMA(1, 0, At, B0); PG8_BAR; PG8_SCHED;
;       PG8_STAGE(PG8_SB(0, 1), b2 + hstepB, voffB);
;       PG8_WAIT_V(6); PG8_BAR; PG8_MMA(1, 1, At, B1); PG8_BAR;
.LBB0_579:
	s_add_i32 s76, s26, 2
	s_add_u32 s28, s2, 0x80
	s_addc_u32 s27, s3, 0
	s_add_i32 s83, 0, 0x10000
	v_add_u32_e32 v156, s83, v173
	ds_read_b128 v[128:131], v156
	ds_read_b128 v[148:151], v156 offset:1024
	ds_read_b128 v[152:155], v156 offset:2048
	ds_read_b128 v[156:159], v156 offset:3072
	s_cmp_eq_u32 s89, s26
	s_cselect_b32 s26, s0, s28
	s_cselect_b32 s27, s1, s27
	s_cselect_b32 s29, s21, s39
	s_cselect_b32 s28, s20, s38
	v_lshl_add_u64 v[196:197], s[2:3], 0, v[144:145]
	s_add_i32 m0, s84, 0xc000
	ds_read_b128 v[160:163], v175
	ds_read_b128 v[164:167], v175 offset:1024
	ds_read_b128 v[168:171], v175 offset:2048
	ds_read_b128 v[176:179], v175 offset:3072
	ds_read_b128 v[180:183], v175 offset:4096
	ds_read_b128 v[184:187], v175 offset:5120
	ds_read_b128 v[188:191], v175 offset:6144
	ds_read_b128 v[192:195], v175 offset:7168
	global_load_lds_dwordx4 v[196:197], off
	v_lshl_add_u64 v[196:197], s[2:3], 0, v[146:147]
	s_add_i32 m0, s84, 0xe000
	s_nop 0
	global_load_lds_dwordx4 v[196:197], off
	s_waitcnt lgkmcnt(8)
	s_barrier
	s_waitcnt lgkmcnt(0)
	s_waitcnt lgkmcnt(0)
	v_mfma_f32_16x16x32_bf16 v[124:127], v[128:131], v[160:163], v[124:127]
	v_mfma_f32_16x16x32_bf16 v[120:123], v[152:155], v[160:163], v[120:123]
	v_mfma_f32_16x16x32_bf16 v[108:111], v[128:131], v[168:171], v[108:111]
	v_mfma_f32_16x16x32_bf16 v[104:107], v[152:155], v[168:171], v[104:107]
	v_mfma_f32_16x16x32_bf16 v[92:95], v[128:131], v[180:183], v[92:95]
	v_mfma_f32_16x16x32_bf16 v[88:91], v[152:155], v[180:183], v[88:91]
	v_mfma_f32_16x16x32_bf16 v[76:79], v[128:131], v[188:191], v[76:79]
	v_mfma_f32_16x16x32_bf16 v[72:75], v[152:155], v[188:191], v[72:75]
	v_mfma_f32_16x16x32_bf16 v[124:127], v[148:151], v[164:167], v[124:127]
	v_mfma_f32_16x16x32_bf16 v[120:123], v[156:159], v[164:167], v[120:123]
	v_mfma_f32_16x16x32_bf16 v[108:111], v[148:151], v[176:179], v[108:111]
	v_mfma_f32_16x16x32_bf16 v[104:107], v[156:159], v[176:179], v[104:107]
	v_mfma_f32_16x16x32_bf16 v[92:95], v[148:151], v[184:187], v[92:95]
	v_mfma_f32_16x16x32_bf16 v[88:91], v[156:159], v[184:187], v[88:91]
	v_mfma_f32_16x16x32_bf16 v[76:79], v[148:151], v[192:195], v[76:79]
	v_mfma_f32_16x16x32_bf16 v[72:75], v[156:159], v[192:195], v[72:75]
	s_barrier
	s_add_i32 s94, 0, 0x14000
	s_add_i32 s83, s83, s97
	v_add_u32_e32 v208, s94, v173
	v_lshl_add_u64 v[212:213], s[28:29], 0, v[132:133]
	s_mov_b32 m0, s83
	ds_read_b128 v[196:199], v208
	ds_read_b128 v[200:203], v208 offset:1024
	ds_read_b128 v[204:207], v208 offset:2048
	ds_read_b128 v[208:211], v208 offset:3072
	global_load_lds_dwordx4 v[212:213], off
	v_lshl_add_u64 v[214:215], s[28:29], 0, v[142:143]
	s_add_i32 m0, s83, 0x2000
	s_nop 0
	global_load_lds_dwordx4 v[214:215], off
	s_barrier
	s_waitcnt lgkmcnt(0)
	s_waitcnt lgkmcnt(0)
	v_mfma_f32_16x16x32_bf16 v[116:119], v[196:199], v[160:163], v[116:119]
	v_mfma_f32_16x16x32_bf16 v[112:115], v[204:207], v[160:163], v[112:115]
	v_mfma_f32_16x16x32_bf16 v[100:103], v[196:199], v[168:171], v[100:103]
	v_mfma_f32_16x16x32_bf16 v[96:99], v[204:207], v[168:171], v[96:99]
	v_mfma_f32_16x16x32_bf16 v[84:87], v[196:199], v[180:183], v[84:87]
	v_mfma_f32_16x16x32_bf16 v[80:83], v[204:207], v[180:183], v[80:83]
	v_mfma_f32_16x16x32_bf16 v[68:71], v[196:199], v[188:191], v[68:71]
	v_mfma_f32_16x16x32_bf16 v[64:67], v[204:207], v[188:191], v[64:67]
	v_mfma_f32_16x16x32_bf16 v[116:119], v[200:203], v[164:167], v[116:119]
	v_mfma_f32_16x16x32_bf16 v[112:115], v[208:211], v[164:167], v[112:115]
	v_mfma_f32_16x16x32_bf16 v[100:103], v[200:203], v[176:179], v[100:103]
	v_mfma_f32_16x16x32_bf16 v[96:99], v[208:211], v[176:179], v[96:99]
	v_mfma_f32_16x16x32_bf16 v[84:87], v[200:203], v[184:187], v[84:87]
	v_mfma_f32_16x16x32_bf16 v[80:83], v[208:211], v[184:187], v[80:83]
	v_mfma_f32_16x16x32_bf16 v[68:71], v[200:203], v[192:195], v[68:71]
	v_mfma_f32_16x16x32_bf16 v[64:67], v[208:211], v[192:195], v[64:67]
	s_mov_b32 m0, s84
	v_lshl_add_u64 v[216:217], s[26:27], 0, v[138:139]
	s_barrier
	ds_read_b128 v[160:163], v175 offset:16384
	ds_read_b128 v[164:167], v175 offset:17408
	ds_read_b128 v[168:171], v175 offset:18432
	ds_read_b128 v[176:179], v175 offset:19456
	ds_read_b128 v[180:183], v175 offset:20480
	ds_read_b128 v[184:187], v175 offset:21504
	ds_read_b128 v[188:191], v175 offset:22528
	ds_read_b128 v[192:195], v175 offset:23552
	global_load_lds_dwordx4 v[216:217], off
	v_lshl_add_u64 v[218:219], s[26:27], 0, v[140:141]
	s_mov_b32 m0, s85
	s_nop 0
	global_load_lds_dwordx4 v[218:219], off
	s_barrier
	s_waitcnt lgkmcnt(0)
	s_waitcnt lgkmcnt(0)
	v_mfma_f32_16x16x32_bf16 v[60:63], v[128:131], v[160:163], v[60:63]
	v_mfma_f32_16x16x32_bf16 v[56:59], v[152:155], v[160:163], v[56:59]
	v_mfma_f32_16x16x32_bf16 v[44:47], v[128:131], v[168:171], v[44:47]
	v_mfma_f32_16x16x32_bf16 v[40:43], v[152:155], v[168:171], v[40:43]
	v_mfma_f32_16x16x32_bf16 v[28:31], v[128:131], v[180:183], v[28:31]
	v_mfma_f32_16x16x32_bf16 v[24:27], v[152:155], v[180:183], v[24:27]
	v_mfma_f32_16x16x32_bf16 v[12:15], v[128:131], v[188:191], v[12:15]
	v_mfma_f32_16x16x32_bf16 v[8:11], v[152:155], v[188:191], v[8:11]
	v_mfma_f32_16x16x32_bf16 v[60:63], v[148:151], v[164:167], v[60:63]
	v_mfma_f32_16x16x32_bf16 v[56:59], v[156:159], v[164:167], v[56:59]
	v_mfma_f32_16x16x32_bf16 v[44:47], v[148:151], v[176:179], v[44:47]
	v_mfma_f32_16x16x32_bf16 v[40:43], v[156:159], v[176:179], v[40:43]
	v_mfma_f32_16x16x32_bf16 v[28:31], v[148:151], v[184:187], v[28:31]
	v_mfma_f32_16x16x32_bf16 v[24:27], v[156:159], v[184:187], v[24:27]
	v_mfma_f32_16x16x32_bf16 v[12:15], v[148:151], v[192:195], v[12:15]
	v_mfma_f32_16x16x32_bf16 v[8:11], v[156:159], v[192:195], v[8:11]
	s_barrier
; #define PG8_STAGE(bufoff, gbase, voff) do { _Pragma("unroll") for (int _i = 0; _i < 2; ++_i) \
;     __builtin_amdgcn_global_load_lds((const unsigned*)((const char*)(gbase) + (voff)[_i]), (LAS unsigned*)(lds + (bufoff) + ldsw + _i * 8192), 16, 0, 0); } while (0)
; #define PG8_LDA(dst, b, h) do { _Pragma("unroll") for (int m = 0; m < 4; ++m) _Pragma("unroll") for (int k = 0; k < 2; ++k) dst[m][k] = *(const LAS bf16x8*)(lds + PG8_SA(b, h) + aoff + m * 2048 + k * 1024); } while (0)
; #define PG8_LDB(dst, b, h) do { _Pragma("unroll") for (int n = 0; n < 2; ++n) _Pragma("unroll") for (int k = 0; k < 2; ++k) dst[n][k] = *(const LAS bf16x8*)(lds + PG8_SB(b, h) + boff + n * 2048 + k * 1024); } while (0)
; #define PG8_MMA(ai, bj, At, Bt) do { __builtin_amdgcn_s_setprio(1); _Pragma("unroll") for (int m = 0; m < 4; ++m) _Pragma("unroll") for (int n = 0; n < 2; ++n) _Pragma("unroll") for (int k = 0; k < 2; ++k) \
;     acc[ai][bj][m][n] = __builtin_amdgcn_mfma_f32_16x16x32_bf16(Bt[n][k], At[m][k], acc[ai][bj][m][n], 0, 0, 0); __builtin_amdgcn_s_setprio(0); } while (0)
; #define PG8_BAR __builtin_amdgcn_s_barrier()
; template <class Epi>
; __device__ __forceinline__ void gemm_phase(LAS unsigned char* lds, const Gemm g, const Epi& E) {
;     ...
;       PG8_LDB(B0, 0, 0); PG8_SCHED; PG8_LDA(At, 0, 0); PG8_STAGE(PG8_SA(1, 1), a1 + hstepA, voffA);
;       PG8_WAIT_L(8); PG8_BAR; PG8_WAIT_L(0); PG8_MMA(0, 0, At, B0); PG8_BAR; PG8_SCHED;
;       PG8_LDB(B1, 0, 1); PG8_STAGE(PG8_SB(0, 0), b2, voffB);
;       PG8_BAR; PG8_WAIT_L(0); PG8_MMA(0, 1, At, B1); PG8_BAR;
;       PG8_LDA(At, 0, 1); PG8_STAGE(PG8_SA(0, 0), a2, voffA);
;       PG8_BAR; PG8_WAIT_L(0); PG8_MMA(1, 0, At, B0); PG8_BAR; PG8_SCHED;
;       PG8_STAGE(PG8_SB(0, 1), b2 + hstepB, voffB);
;       PG8_WAIT_V(6); PG8_BAR; PG8_MMA(1, 1, At, B1); PG8_BAR;
;       PG8_LDB(B0, 1, 0); PG8_SCHED; PG8_LDA(At, 1, 0); PG8_STAGE(PG8_SA(0, 1), a2 + hstepA, voffA);
;       PG8_WAIT_L(8); PG8_BAR; PG8_WAIT_L(0); PG8_MMA(0, 0, At, B0); PG8_BAR; PG8_SCHED;
;       PG8_LDB(B1, 1, 1); PG8_STAGE(PG8_SB(1, 0), b3, voffB);
;       PG8_BAR; PG8_WAIT_L(0); PG8_MMA(0, 1, At, B1); PG8_BAR;
;       PG8_LDA(At, 1, 1); PG8_STAGE(PG8_SA(1, 0), a3, voffA);
;       PG8_BAR; PG8_WAIT_L(0); PG8_MMA(1, 0, At, B0); PG8_BAR; PG8_SCHED;
;       PG8_STAGE(PG8_SB(1, 1), b3 + hstepB, voffB);
;       PG8_WAIT_V(6); PG8_BAR; PG8_MMA(1, 1, At, B1); PG8_BAR;
	s_add_u32 s28, s28, s95
	s_addc_u32 s29, s29, 0
	s_add_i32 s83, s94, s97
	v_lshl_add_u64 v[220:221], s[28:29], 0, v[132:133]
	s_mov_b32 m0, s83
	v_lshl_add_u64 v[222:223], s[28:29], 0, v[142:143]
	global_load_lds_dwordx4 v[220:221], off
	s_add_i32 m0, s83, 0x2000
	s_nop 0
	global_load_lds_dwordx4 v[222:223], off
	s_waitcnt vmcnt(6)
	s_barrier
	v_mfma_f32_16x16x32_bf16 v[52:55], v[196:199], v[160:163], v[52:55]
	v_mfma_f32_16x16x32_bf16 v[48:51], v[204:207], v[160:163], v[48:51]
	v_mfma_f32_16x16x32_bf16 v[36:39], v[196:199], v[168:171], v[36:39]
	v_mfma_f32_16x16x32_bf16 v[32:35], v[204:207], v[168:171], v[32:35]
	v_mfma_f32_16x16x32_bf16 v[20:23], v[196:199], v[180:183], v[20:23]
	v_mfma_f32_16x16x32_bf16 v[16:19], v[204:207], v[180:183], v[16:19]
	v_mfma_f32_16x16x32_bf16 v[4:7], v[196:199], v[188:191], v[4:7]
	v_mfma_f32_16x16x32_bf16 v[0:3], v[204:207], v[188:191], v[0:3]
	v_mfma_f32_16x16x32_bf16 v[52:55], v[200:203], v[164:167], v[52:55]
	v_mfma_f32_16x16x32_bf16 v[48:51], v[208:211], v[164:167], v[48:51]
	v_mfma_f32_16x16x32_bf16 v[36:39], v[200:203], v[176:179], v[36:39]
	v_mfma_f32_16x16x32_bf16 v[32:35], v[208:211], v[176:179], v[32:35]
	v_mfma_f32_16x16x32_bf16 v[20:23], v[200:203], v[184:187], v[20:23]
	v_mfma_f32_16x16x32_bf16 v[16:19], v[208:211], v[184:187], v[16:19]
	v_mfma_f32_16x16x32_bf16 v[4:7], v[200:203], v[192:195], v[4:7]
	v_mfma_f32_16x16x32_bf16 v[0:3], v[208:211], v[192:195], v[0:3]
	s_add_i32 s28, 0, 0x18000
	v_add_u32_e32 v156, s28, v173
	s_barrier
	ds_read_b128 v[128:131], v156
	ds_read_b128 v[148:151], v156 offset:1024
	ds_read_b128 v[152:155], v156 offset:2048
	ds_read_b128 v[156:159], v156 offset:3072
	s_add_u32 s26, s26, s56
	s_addc_u32 s27, s27, 0
	s_mov_b32 m0, s86
	v_lshl_add_u64 v[196:197], s[26:27], 0, v[138:139]
	ds_read_b128 v[160:163], v175 offset:32768
	ds_read_b128 v[164:167], v175 offset:33792
	ds_read_b128 v[168:171], v175 offset:34816
	ds_read_b128 v[176:179], v175 offset:35840
	ds_read_b128 v[180:183], v175 offset:36864
	ds_read_b128 v[184:187], v175 offset:37888
	ds_read_b128 v[188:191], v175 offset:38912
	ds_read_b128 v[192:195], v175 offset:39936
	global_load_lds_dwordx4 v[196:197], off
	v_lshl_add_u64 v[196:197], s[26:27], 0, v[140:141]
	s_mov_b32 m0, s87
	s_nop 0
	global_load_lds_dwordx4 v[196:197], off
	s_waitcnt lgkmcnt(8)
	s_barrier
	s_waitcnt lgkmcnt(0)
	s_waitcnt lgkmcnt(0)
	v_mfma_f32_16x16x32_bf16 v[124:127], v[128:131], v[160:163], v[124:127]
	v_mfma_f32_16x16x32_bf16 v[120:123], v[152:155], v[160:163], v[120:123]
	v_mfma_f32_16x16x32_bf16 v[108:111], v[128:131], v[168:171], v[108:111]
	v_mfma_f32_16x16x32_bf16 v[104:107], v[152:155], v[168:171], v[104:107]
	v_mfma_f32_16x16x32_bf16 v[92:95], v[128:131], v[180:183], v[92:95]
	v_mfma_f32_16x16x32_bf16 v[88:91], v[152:155], v[180:183], v[88:91]
	v_mfma_f32_16x16x32_bf16 v[76:79], v[128:131], v[188:191], v[76:79]
	v_mfma_f32_16x16x32_bf16 v[72:75], v[152:155], v[188:191], v[72:75]
	v_mfma_f32_16x16x32_bf16 v[124:127], v[148:151], v[164:167], v[124:127]
	v_mfma_f32_16x16x32_bf16 v[120:123], v[156:159], v[164:167], v[120:123]
	v_mfma_f32_16x16x32_bf16 v[108:111], v[148:151], v[176:179], v[108:111]
	v_mfma_f32_16x16x32_bf16 v[104:107], v[156:159], v[176:179], v[104:107]
	v_mfma_f32_16x16x32_bf16 v[92:95], v[148:151], v[184:187], v[92:95]
	v_mfma_f32_16x16x32_bf16 v[88:91], v[156:159], v[184:187], v[88:91]
	v_mfma_f32_16x16x32_bf16 v[76:79], v[148:151], v[192:195], v[76:79]
	v_mfma_f32_16x16x32_bf16 v[72:75], v[156:159], v[192:195], v[72:75]
	s_barrier
	s_add_i32 s26, 0, 0x1c000
	s_add_i32 s27, s28, s97
	v_add_u32_e32 v208, s26, v173
	v_lshl_add_u64 v[212:213], v[212:213], 0, s[22:23]
	s_mov_b32 m0, s27
	ds_read_b128 v[196:199], v208
	ds_read_b128 v[200:203], v208 offset:1024
	ds_read_b128 v[204:207], v208 offset:2048
	ds_read_b128 v[208:211], v208 offset:3072
	global_load_lds_dwordx4 v[212:213], off
	v_lshl_add_u64 v[212:213], v[214:215], 0, s[22:23]
	s_add_i32 m0, s27, 0x2000
	s_nop 0
	global_load_lds_dwordx4 v[212:213], off
	s_barrier
; #define PG8_STAGE(bufoff, gbase, voff) do { _Pragma("unroll") for (int _i = 0; _i < 2; ++_i) \
;     __builtin_amdgcn_global_load_lds((const unsigned*)((const char*)(gbase) + (voff)[_i]), (LAS unsigned*)(lds + (bufoff) + ldsw + _i * 8192), 16, 0, 0); } while (0)
; #define PG8_LDA(dst, b, h) do { _Pragma("unroll") for (int m = 0; m < 4; ++m) _Pragma("unroll") for (int k = 0; k < 2; ++k) dst[m][k] = *(const LAS bf16x8*)(lds + PG8_SA(b, h) + aoff + m * 2048 + k * 1024); } while (0)
; #define PG8_LDB(dst, b, h) do { _Pragma("unroll") for (int n = 0; n < 2; ++n) _Pragma("unroll") for (int k = 0; k < 2; ++k) dst[n][k] = *(const LAS bf16x8*)(lds + PG8_SB(b, h) + boff + n * 2048 + k * 1024); } while (0)
; #define PG8_MMA(ai, bj, At, Bt) do { __builtin_amdgcn_s_setprio(1); _Pragma("unroll") for (int m = 0; m < 4; ++m) _Pragma("unroll") for (int n = 0; n < 2; ++n) _Pragma("unroll") for (int k = 0; k < 2; ++k) \
;     acc[ai][bj][m][n] = __builtin_amdgcn_mfma_f32_16x16x32_bf16(Bt[n][k], At[m][k], acc[ai][bj][m][n], 0, 0, 0); __builtin_amdgcn_s_setprio(0); } while (0)
; #define PG8_WAIT_V(n) asm volatile("s_waitcnt vmcnt(" #n ")" ::: "memory")
; #define PG8_WAIT_L(n) asm volatile("s_waitcnt lgkmcnt(" #n ")" ::: "memory")
; #define PG8_BAR __builtin_amdgcn_s_barrier()
; #define PG8_SCHED __builtin_amdgcn_sched_barrier(0)
; template <class Epi>
; __device__ __forceinline__ void gemm_phase(LAS unsigned char* lds, const Gemm g, const Epi& E) {
;     ...
;       PG8_WAIT_V(6); PG8_BAR; PG8_MMA(1, 1, At, B1); PG8_BAR;
;       PG8_LDB(B0, 1, 0); PG8_SCHED; PG8_LDA(At, 1, 0); PG8_STAGE(PG8_SA(0, 1), a2 + hstepA, voffA);
;       PG8_WAIT_L(8); PG8_BAR; PG8_WAIT_L(0); PG8_MMA(0, 0, At, B0); PG8_BAR; PG8_SCHED;
;       PG8_LDB(B1, 1, 1); PG8_STAGE(PG8_SB(1, 0), b3, voffB);
;       PG8_BAR; PG8_WAIT_L(0); PG8_MMA(0, 1, At, B1); PG8_BAR;
;       PG8_LDA(At, 1, 1); PG8_STAGE(PG8_SA(1, 0), a3, voffA);
;       PG8_BAR; PG8_WAIT_L(0); PG8_MMA(1, 0, At, B0); PG8_BAR; PG8_SCHED;
;       PG8_STAGE(PG8_SB(1, 1), b3 + hstepB, voffB);
;       PG8_WAIT_V(6); PG8_BAR; PG8_MMA(1, 1, At, B1); PG8_BAR;
;     }
	s_waitcnt lgkmcnt(0)
	s_waitcnt lgkmcnt(0)
	v_mfma_f32_16x16x32_bf16 v[116:119], v[196:199], v[160:163], v[116:119]
	v_mfma_f32_16x16x32_bf16 v[112:115], v[204:207], v[160:163], v[112:115]
	v_mfma_f32_16x16x32_bf16 v[100:103], v[196:199], v[168:171], v[100:103]
	v_mfma_f32_16x16x32_bf16 v[96:99], v[204:207], v[168:171], v[96:99]
	v_mfma_f32_16x16x32_bf16 v[84:87], v[196:199], v[180:183], v[84:87]
	v_mfma_f32_16x16x32_bf16 v[80:83], v[204:207], v[180:183], v[80:83]
	v_mfma_f32_16x16x32_bf16 v[68:71], v[196:199], v[188:191], v[68:71]
	v_mfma_f32_16x16x32_bf16 v[64:67], v[204:207], v[188:191], v[64:67]
	v_mfma_f32_16x16x32_bf16 v[116:119], v[200:203], v[164:167], v[116:119]
	v_mfma_f32_16x16x32_bf16 v[112:115], v[208:211], v[164:167], v[112:115]
	v_mfma_f32_16x16x32_bf16 v[100:103], v[200:203], v[176:179], v[100:103]
	v_mfma_f32_16x16x32_bf16 v[96:99], v[208:211], v[176:179], v[96:99]
	v_mfma_f32_16x16x32_bf16 v[84:87], v[200:203], v[184:187], v[84:87]
	v_mfma_f32_16x16x32_bf16 v[80:83], v[208:211], v[184:187], v[80:83]
	v_mfma_f32_16x16x32_bf16 v[68:71], v[200:203], v[192:195], v[68:71]
	v_mfma_f32_16x16x32_bf16 v[64:67], v[208:211], v[192:195], v[64:67]
	s_mov_b32 m0, s74
	v_lshl_add_u64 v[212:213], v[216:217], 0, s[22:23]
	s_barrier
	ds_read_b128 v[160:163], v175 offset:49152
	ds_read_b128 v[164:167], v175 offset:50176
	ds_read_b128 v[168:171], v175 offset:51200
	ds_read_b128 v[176:179], v175 offset:52224
	ds_read_b128 v[180:183], v175 offset:53248
	ds_read_b128 v[184:187], v175 offset:54272
	ds_read_b128 v[188:191], v175 offset:55296
	ds_read_b128 v[192:195], v175 offset:56320
	global_load_lds_dwordx4 v[212:213], off
	v_lshl_add_u64 v[212:213], v[218:219], 0, s[22:23]
	s_mov_b32 m0, s78
	s_nop 0
	global_load_lds_dwordx4 v[212:213], off
	s_barrier
	s_waitcnt lgkmcnt(0)
	s_waitcnt lgkmcnt(0)
	v_mfma_f32_16x16x32_bf16 v[60:63], v[128:131], v[160:163], v[60:63]
	v_mfma_f32_16x16x32_bf16 v[56:59], v[152:155], v[160:163], v[56:59]
	v_mfma_f32_16x16x32_bf16 v[44:47], v[128:131], v[168:171], v[44:47]
	v_mfma_f32_16x16x32_bf16 v[40:43], v[152:155], v[168:171], v[40:43]
	v_mfma_f32_16x16x32_bf16 v[28:31], v[128:131], v[180:183], v[28:31]
	v_mfma_f32_16x16x32_bf16 v[24:27], v[152:155], v[180:183], v[24:27]
	v_mfma_f32_16x16x32_bf16 v[12:15], v[128:131], v[188:191], v[12:15]
	v_mfma_f32_16x16x32_bf16 v[8:11], v[152:155], v[188:191], v[8:11]
	v_mfma_f32_16x16x32_bf16 v[60:63], v[148:151], v[164:167], v[60:63]
	v_mfma_f32_16x16x32_bf16 v[56:59], v[156:159], v[164:167], v[56:59]
	v_mfma_f32_16x16x32_bf16 v[44:47], v[148:151], v[176:179], v[44:47]
	v_mfma_f32_16x16x32_bf16 v[40:43], v[156:159], v[176:179], v[40:43]
	v_mfma_f32_16x16x32_bf16 v[28:31], v[148:151], v[184:187], v[28:31]
	v_mfma_f32_16x16x32_bf16 v[24:27], v[156:159], v[184:187], v[24:27]
	v_mfma_f32_16x16x32_bf16 v[12:15], v[148:151], v[192:195], v[12:15]
	v_mfma_f32_16x16x32_bf16 v[8:11], v[156:159], v[192:195], v[8:11]
	s_barrier
	s_add_i32 s26, s26, s97
	v_lshl_add_u64 v[128:129], v[220:221], 0, s[22:23]
	s_mov_b32 m0, s26
	s_nop 0
	global_load_lds_dwordx4 v[128:129], off
	v_lshl_add_u64 v[128:129], v[222:223], 0, s[22:23]
	s_add_i32 m0, s26, 0x2000
	s_nop 0
	global_load_lds_dwordx4 v[128:129], off
	s_waitcnt vmcnt(6)
	s_barrier
	v_mfma_f32_16x16x32_bf16 v[52:55], v[196:199], v[160:163], v[52:55]
	v_mfma_f32_16x16x32_bf16 v[48:51], v[204:207], v[160:163], v[48:51]
	v_mfma_f32_16x16x32_bf16 v[36:39], v[196:199], v[168:171], v[36:39]
	v_mfma_f32_16x16x32_bf16 v[32:35], v[204:207], v[168:171], v[32:35]
	v_mfma_f32_16x16x32_bf16 v[20:23], v[196:199], v[180:183], v[20:23]
	v_mfma_f32_16x16x32_bf16 v[16:19], v[204:207], v[180:183], v[16:19]
	v_mfma_f32_16x16x32_bf16 v[4:7], v[196:199], v[188:191], v[4:7]
	v_mfma_f32_16x16x32_bf16 v[0:3], v[204:207], v[188:191], v[0:3]
	v_mfma_f32_16x16x32_bf16 v[52:55], v[200:203], v[164:167], v[52:55]
	v_mfma_f32_16x16x32_bf16 v[48:51], v[208:211], v[164:167], v[48:51]
	v_mfma_f32_16x16x32_bf16 v[36:39], v[200:203], v[176:179], v[36:39]
	v_mfma_f32_16x16x32_bf16 v[32:35], v[208:211], v[176:179], v[32:35]
	v_mfma_f32_16x16x32_bf16 v[20:23], v[200:203], v[184:187], v[20:23]
	v_mfma_f32_16x16x32_bf16 v[16:19], v[208:211], v[184:187], v[16:19]
	v_mfma_f32_16x16x32_bf16 v[4:7], v[200:203], v[192:195], v[4:7]
	v_mfma_f32_16x16x32_bf16 v[0:3], v[208:211], v[192:195], v[0:3]
	s_add_u32 s2, s2, 0x100
	s_addc_u32 s3, s3, 0
	s_add_u32 s38, s38, 0x100
	s_addc_u32 s39, s39, 0
	s_cmp_ge_u32 s76, s72
	s_mov_b32 s26, s76
	s_barrier
	s_cbranch_scc0 .LBB0_579

; #define PG8_STAGE(bufoff, gbase, voff) do { _Pragma("unroll") for (int _i = 0; _i < 2; ++_i) \
;     __builtin_amdgcn_global_load_lds((const unsigned*)((const char*)(gbase) + (voff)[_i]), (LAS unsigned*)(lds + (bufoff) + ldsw + _i * 8192), 16, 0, 0); } while (0)
; #define PG8_LDA(dst, b, h) do { _Pragma("unroll") for (int m = 0; m < 4; ++m) _Pragma("unroll") for (int k = 0; k < 2; ++k) dst[m][k] = *(const LAS bf16x8*)(lds + PG8_SA(b, h) + aoff + m * 2048 + k * 1024); } while (0)
; #define PG8_LDB(dst, b, h) do { _Pragma("unroll") for (int n = 0; n < 2; ++n) _Pragma("unroll") for (int k = 0; k < 2; ++k) dst[n][k] = *(const LAS bf16x8*)(lds + PG8_SB(b, h) + boff + n * 2048 + k * 1024); } while (0)
; #define PG8_WAIT_L(n) asm volatile("s_waitcnt lgkmcnt(" #n ")" ::: "memory")
; #define PG8_BAR __builtin_amdgcn_s_barrier()
; #define PG8_SCHED __builtin_amdgcn_sched_barrier(0)
; template <class Epi>
; __device__ __forceinline__ void gemm_phase(LAS unsigned char* lds, const Gemm g, const Epi& E) {
;     ...
;     const bool has_next = S.next(ui + 1, nxt);
;     const char* nA = has_next ? (const char*)(nxt.w ? g.A2 : g.A) + (size_t)nxt.pm * tstepA : cA; const char* nB = has_next ? (const char*)(nxt.w ? g.Bt2 : g.Bt) + (size_t)nxt.pn * tstepB : cB;
;     for (int t = 0; t < nt; t += 2) {
;       const bool last = (t == nt - 2);
;       const char* a1 = cA + (size_t)(t + 1) * kstep;
;       const char* a2 = last ? nA : cA + (size_t)(t + 2) * kstep; const char* b2 = last ? nB : cB + (size_t)(t + 2) * kstep;
;       const char* a3 = a2 + kstep; const char* b3 = b2 + kstep;
;       PG8_LDB(B0, 0, 0); PG8_SCHED; PG8_LDA(At, 0, 0); PG8_STAGE(PG8_SA(1, 1), a1 + hstepA, voffA);
;       PG8_WAIT_L(8); PG8_BAR; PG8_WAIT_L(0); PG8_MMA(0, 0, At, B0); PG8_BAR; PG8_SCHED;
;       PG8_LDB(B1, 0, 1); PG8_STAGE(PG8_SB(0, 0), b2, voffB);
;       PG8_BAR; PG8_WAIT_L(0); PG8_MMA(0, 1, At, B1); PG8_BAR;
;       PG8_LDA(At, 0, 1); PG8_STAGE(PG8_SA(0, 0), a2, voffA);
;       PG8_BAR; PG8_WAIT_L(0); PG8_MMA(1, 0, At, B0); PG8_BAR; PG8_SCHED;
;     ...
; #pragma unroll
;     for (int a = 0; a < 2; ++a)
; #pragma unroll
;       for (int b = 0; b < 2; ++b)
; #pragma unroll
;         for (int m = 0; m < 4; ++m)
; #pragma unroll
;           for (int n = 0; n < 2; ++n) acc[a][b][m][n] = (f32x4){0.f, 0.f, 0.f, 0.f};
;     cur = nxt; cA = nA; cB = nB; ++ui;
.Lpeel:
	s_add_i32 s76, s26, 2
	s_add_u32 s28, s2, 0x80
	s_addc_u32 s27, s3, 0
	s_add_i32 s83, 0, 0x10000
	v_add_u32_e32 v156, s83, v173
	ds_read_b128 v[128:131], v156
	ds_read_b128 v[148:151], v156 offset:1024
	ds_read_b128 v[152:155], v156 offset:2048
	ds_read_b128 v[156:159], v156 offset:3072
	s_cmp_eq_u32 s89, s26
	s_cselect_b32 s26, s0, s28
	s_cselect_b32 s27, s1, s27
	s_cselect_b32 s29, s21, s39
	s_cselect_b32 s28, s20, s38
	v_lshl_add_u64 v[196:197], s[2:3], 0, v[144:145]
	s_add_i32 m0, s84, 0xc000
	ds_read_b128 v[160:163], v175
	ds_read_b128 v[164:167], v175 offset:1024
	ds_read_b128 v[168:171], v175 offset:2048
	ds_read_b128 v[176:179], v175 offset:3072
	ds_read_b128 v[180:183], v175 offset:4096
	ds_read_b128 v[184:187], v175 offset:5120
	ds_read_b128 v[188:191], v175 offset:6144
	ds_read_b128 v[192:195], v175 offset:7168
	global_load_lds_dwordx4 v[196:197], off
	v_lshl_add_u64 v[196:197], s[2:3], 0, v[146:147]
	s_add_i32 m0, s84, 0xe000
	s_nop 0
	global_load_lds_dwordx4 v[196:197], off
	s_waitcnt lgkmcnt(8)
	s_barrier
	s_waitcnt lgkmcnt(0)
	s_waitcnt lgkmcnt(0)
	v_mfma_f32_16x16x32_bf16 v[124:127], v[128:131], v[160:163], 0
	v_mfma_f32_16x16x32_bf16 v[120:123], v[152:155], v[160:163], 0
	v_mfma_f32_16x16x32_bf16 v[108:111], v[128:131], v[168:171], 0
	v_mfma_f32_16x16x32_bf16 v[104:107], v[152:155], v[168:171], 0
	v_mfma_f32_16x16x32_bf16 v[92:95], v[128:131], v[180:183], 0
	v_mfma_f32_16x16x32_bf16 v[88:91], v[152:155], v[180:183], 0
	v_mfma_f32_16x16x32_bf16 v[76:79], v[128:131], v[188:191], 0
	v_mfma_f32_16x16x32_bf16 v[72:75], v[152:155], v[188:191], 0
	v_mfma_f32_16x16x32_bf16 v[124:127], v[148:151], v[164:167], v[124:127]
	v_mfma_f32_16x16x32_bf16 v[120:123], v[156:159], v[164:167], v[120:123]
	v_mfma_f32_16x16x32_bf16 v[108:111], v[148:151], v[176:179], v[108:111]
	v_mfma_f32_16x16x32_bf16 v[104:107], v[156:159], v[176:179], v[104:107]
	v_mfma_f32_16x16x32_bf16 v[92:95], v[148:151], v[184:187], v[92:95]
	v_mfma_f32_16x16x32_bf16 v[88:91], v[156:159], v[184:187], v[88:91]
	v_mfma_f32_16x16x32_bf16 v[76:79], v[148:151], v[192:195], v[76:79]
	v_mfma_f32_16x16x32_bf16 v[72:75], v[156:159], v[192:195], v[72:75]
	s_barrier
	s_add_i32 s94, 0, 0x14000
	s_add_i32 s83, s83, s97
	v_add_u32_e32 v208, s94, v173
	v_lshl_add_u64 v[212:213], s[28:29], 0, v[132:133]
	s_mov_b32 m0, s83
	ds_read_b128 v[196:199], v208
	ds_read_b128 v[200:203], v208 offset:1024
	ds_read_b128 v[204:207], v208 offset:2048
	ds_read_b128 v[208:211], v208 offset:3072
	global_load_lds_dwordx4 v[212:213], off
	v_lshl_add_u64 v[214:215], s[28:29], 0, v[142:143]
	s_add_i32 m0, s83, 0x2000
	s_nop 0
	global_load_lds_dwordx4 v[214:215], off
	s_barrier
	s_waitcnt lgkmcnt(0)
	s_waitcnt lgkmcnt(0)
	v_mfma_f32_16x16x32_bf16 v[116:119], v[196:199], v[160:163], 0
	v_mfma_f32_16x16x32_bf16 v[112:115], v[204:207], v[160:163], 0
	v_mfma_f32_16x16x32_bf16 v[100:103], v[196:199], v[168:171], 0
	v_mfma_f32_16x16x32_bf16 v[96:99], v[204:207], v[168:171], 0
	v_mfma_f32_16x16x32_bf16 v[84:87], v[196:199], v[180:183], 0
	v_mfma_f32_16x16x32_bf16 v[80:83], v[204:207], v[180:183], 0
	v_mfma_f32_16x16x32_bf16 v[68:71], v[196:199], v[188:191], 0
	v_mfma_f32_16x16x32_bf16 v[64:67], v[204:207], v[188:191], 0
	v_mfma_f32_16x16x32_bf16 v[116:119], v[200:203], v[164:167], v[116:119]
	v_mfma_f32_16x16x32_bf16 v[112:115], v[208:211], v[164:167], v[112:115]
	v_mfma_f32_16x16x32_bf16 v[100:103], v[200:203], v[176:179], v[100:103]
	v_mfma_f32_16x16x32_bf16 v[96:99], v[208:211], v[176:179], v[96:99]
	v_mfma_f32_16x16x32_bf16 v[84:87], v[200:203], v[184:187], v[84:87]
	v_mfma_f32_16x16x32_bf16 v[80:83], v[208:211], v[184:187], v[80:83]
	v_mfma_f32_16x16x32_bf16 v[68:71], v[200:203], v[192:195], v[68:71]
	v_mfma_f32_16x16x32_bf16 v[64:67], v[208:211], v[192:195], v[64:67]
	s_mov_b32 m0, s84
	v_lshl_add_u64 v[216:217], s[26:27], 0, v[138:139]
	s_barrier
	ds_read_b128 v[160:163], v175 offset:16384
	ds_read_b128 v[164:167], v175 offset:17408
	ds_read_b128 v[168:171], v175 offset:18432
	ds_read_b128 v[176:179], v175 offset:19456
	ds_read_b128 v[180:183], v175 offset:20480
	ds_read_b128 v[184:187], v175 offset:21504
	ds_read_b128 v[188:191], v175 offset:22528
	ds_read_b128 v[192:195], v175 offset:23552
	global_load_lds_dwordx4 v[216:217], off
	v_lshl_add_u64 v[218:219], s[26:27], 0, v[140:141]
	s_mov_b32 m0, s85
	s_nop 0
	global_load_lds_dwordx4 v[218:219], off
	s_barrier
	s_waitcnt lgkmcnt(0)
	s_waitcnt lgkmcnt(0)
	v_mfma_f32_16x16x32_bf16 v[60:63], v[128:131], v[160:163], 0
	v_mfma_f32_16x16x32_bf16 v[56:59], v[152:155], v[160:163], 0
	v_mfma_f32_16x16x32_bf16 v[44:47], v[128:131], v[168:171], 0
	v_mfma_f32_16x16x32_bf16 v[40:43], v[152:155], v[168:171], 0
	v_mfma_f32_16x16x32_bf16 v[28:31], v[128:131], v[180:183], 0
	v_mfma_f32_16x16x32_bf16 v[24:27], v[152:155], v[180:183], 0
	v_mfma_f32_16x16x32_bf16 v[12:15], v[128:131], v[188:191], 0
	v_mfma_f32_16x16x32_bf16 v[8:11], v[152:155], v[188:191], 0
	v_mfma_f32_16x16x32_bf16 v[60:63], v[148:151], v[164:167], v[60:63]
	v_mfma_f32_16x16x32_bf16 v[56:59], v[156:159], v[164:167], v[56:59]
	v_mfma_f32_16x16x32_bf16 v[44:47], v[148:151], v[176:179], v[44:47]
	v_mfma_f32_16x16x32_bf16 v[40:43], v[156:159], v[176:179], v[40:43]
	v_mfma_f32_16x16x32_bf16 v[28:31], v[148:151], v[184:187], v[28:31]
	v_mfma_f32_16x16x32_bf16 v[24:27], v[156:159], v[184:187], v[24:27]
	v_mfma_f32_16x16x32_bf16 v[12:15], v[148:151], v[192:195], v[12:15]
	v_mfma_f32_16x16x32_bf16 v[8:11], v[156:159], v[192:195], v[8:11]
	s_barrier
; #define PG8_STAGE(bufoff, gbase, voff) do { _Pragma("unroll") for (int _i = 0; _i < 2; ++_i) \
;     __builtin_amdgcn_global_load_lds((const unsigned*)((const char*)(gbase) + (voff)[_i]), (LAS unsigned*)(lds + (bufoff) + ldsw + _i * 8192), 16, 0, 0); } while (0)
; #define PG8_LDA(dst, b, h) do { _Pragma("unroll") for (int m = 0; m < 4; ++m) _Pragma("unroll") for (int k = 0; k < 2; ++k) dst[m][k] = *(const LAS bf16x8*)(lds + PG8_SA(b, h) + aoff + m * 2048 + k * 1024); } while (0)
; #define PG8_LDB(dst, b, h) do { _Pragma("unroll") for (int n = 0; n < 2; ++n) _Pragma("unroll") for (int k = 0; k < 2; ++k) dst[n][k] = *(const LAS bf16x8*)(lds + PG8_SB(b, h) + boff + n * 2048 + k * 1024); } while (0)
; #define PG8_MMA(ai, bj, At, Bt) do { __builtin_amdgcn_s_setprio(1); _Pragma("unroll") for (int m = 0; m < 4; ++m) _Pragma("unroll") for (int n = 0; n < 2; ++n) _Pragma("unroll") for (int k = 0; k < 2; ++k) \
;     acc[ai][bj][m][n] = __builtin_amdgcn_mfma_f32_16x16x32_bf16(Bt[n][k], At[m][k], acc[ai][bj][m][n], 0, 0, 0); __builtin_amdgcn_s_setprio(0); } while (0)
; #define PG8_WAIT_V(n) asm volatile("s_waitcnt vmcnt(" #n ")" ::: "memory")
; #define PG8_WAIT_L(n) asm volatile("s_waitcnt lgkmcnt(" #n ")" ::: "memory")
; #define PG8_BAR __builtin_amdgcn_s_barrier()
; #define PG8_SCHED __builtin_amdgcn_sched_barrier(0)
; template <class Epi>
; __device__ __forceinline__ void gemm_phase(LAS unsigned char* lds, const Gemm g, const Epi& E) {
;     ...
;       PG8_BAR; PG8_WAIT_L(0); PG8_MMA(1, 0, At, B0); PG8_BAR; PG8_SCHED;
;       PG8_STAGE(PG8_SB(0, 1), b2 + hstepB, voffB);
;       PG8_WAIT_V(6); PG8_BAR; PG8_MMA(1, 1, At, B1); PG8_BAR;
;       PG8_LDB(B0, 1, 0); PG8_SCHED; PG8_LDA(At, 1, 0); PG8_STAGE(PG8_SA(0, 1), a2 + hstepA, voffA);
;       PG8_WAIT_L(8); PG8_BAR; PG8_WAIT_L(0); PG8_MMA(0, 0, At, B0); PG8_BAR; PG8_SCHED;
;       PG8_LDB(B1, 1, 1); PG8_STAGE(PG8_SB(1, 0), b3, voffB);
;       PG8_BAR; PG8_WAIT_L(0); PG8_MMA(0, 1, At, B1); PG8_BAR;
	s_add_u32 s28, s28, s95
	s_addc_u32 s29, s29, 0
	s_add_i32 s83, s94, s97
	v_lshl_add_u64 v[220:221], s[28:29], 0, v[132:133]
	s_mov_b32 m0, s83
	v_lshl_add_u64 v[222:223], s[28:29], 0, v[142:143]
	global_load_lds_dwordx4 v[220:221], off
	s_add_i32 m0, s83, 0x2000
	s_nop 0
	global_load_lds_dwordx4 v[222:223], off
	s_waitcnt vmcnt(24)
	s_barrier
	v_mfma_f32_16x16x32_bf16 v[52:55], v[196:199], v[160:163], 0
	v_mfma_f32_16x16x32_bf16 v[48:51], v[204:207], v[160:163], 0
	v_mfma_f32_16x16x32_bf16 v[36:39], v[196:199], v[168:171], 0
	v_mfma_f32_16x16x32_bf16 v[32:35], v[204:207], v[168:171], 0
	v_mfma_f32_16x16x32_bf16 v[20:23], v[196:199], v[180:183], 0
	v_mfma_f32_16x16x32_bf16 v[16:19], v[204:207], v[180:183], 0
	v_mfma_f32_16x16x32_bf16 v[4:7], v[196:199], v[188:191], 0
	v_mfma_f32_16x16x32_bf16 v[0:3], v[204:207], v[188:191], 0
	v_mfma_f32_16x16x32_bf16 v[52:55], v[200:203], v[164:167], v[52:55]
	v_mfma_f32_16x16x32_bf16 v[48:51], v[208:211], v[164:167], v[48:51]
	v_mfma_f32_16x16x32_bf16 v[36:39], v[200:203], v[176:179], v[36:39]
	v_mfma_f32_16x16x32_bf16 v[32:35], v[208:211], v[176:179], v[32:35]
	v_mfma_f32_16x16x32_bf16 v[20:23], v[200:203], v[184:187], v[20:23]
	v_mfma_f32_16x16x32_bf16 v[16:19], v[208:211], v[184:187], v[16:19]
	v_mfma_f32_16x16x32_bf16 v[4:7], v[200:203], v[192:195], v[4:7]
	v_mfma_f32_16x16x32_bf16 v[0:3], v[208:211], v[192:195], v[0:3]
	s_add_i32 s28, 0, 0x18000
	v_add_u32_e32 v156, s28, v173
	s_barrier
	ds_read_b128 v[128:131], v156
	ds_read_b128 v[148:151], v156 offset:1024
	ds_read_b128 v[152:155], v156 offset:2048
	ds_read_b128 v[156:159], v156 offset:3072
	s_add_u32 s26, s26, s56
	s_addc_u32 s27, s27, 0
	s_mov_b32 m0, s86
	v_lshl_add_u64 v[196:197], s[26:27], 0, v[138:139]
	ds_read_b128 v[160:163], v175 offset:32768
	ds_read_b128 v[164:167], v175 offset:33792
	ds_read_b128 v[168:171], v175 offset:34816
	ds_read_b128 v[176:179], v175 offset:35840
	ds_read_b128 v[180:183], v175 offset:36864
	ds_read_b128 v[184:187], v175 offset:37888
	ds_read_b128 v[188:191], v175 offset:38912
	ds_read_b128 v[192:195], v175 offset:39936
	global_load_lds_dwordx4 v[196:197], off
	v_lshl_add_u64 v[196:197], s[26:27], 0, v[140:141]
	s_mov_b32 m0, s87
	s_nop 0
	global_load_lds_dwordx4 v[196:197], off
	s_waitcnt lgkmcnt(8)
	s_barrier
	s_waitcnt lgkmcnt(0)
	s_waitcnt lgkmcnt(0)
	v_mfma_f32_16x16x32_bf16 v[124:127], v[128:131], v[160:163], v[124:127]
	v_mfma_f32_16x16x32_bf16 v[120:123], v[152:155], v[160:163], v[120:123]
	v_mfma_f32_16x16x32_bf16 v[108:111], v[128:131], v[168:171], v[108:111]
	v_mfma_f32_16x16x32_bf16 v[104:107], v[152:155], v[168:171], v[104:107]
	v_mfma_f32_16x16x32_bf16 v[92:95], v[128:131], v[180:183], v[92:95]
	v_mfma_f32_16x16x32_bf16 v[88:91], v[152:155], v[180:183], v[88:91]
	v_mfma_f32_16x16x32_bf16 v[76:79], v[128:131], v[188:191], v[76:79]
	v_mfma_f32_16x16x32_bf16 v[72:75], v[152:155], v[188:191], v[72:75]
	v_mfma_f32_16x16x32_bf16 v[124:127], v[148:151], v[164:167], v[124:127]
	v_mfma_f32_16x16x32_bf16 v[120:123], v[156:159], v[164:167], v[120:123]
	v_mfma_f32_16x16x32_bf16 v[108:111], v[148:151], v[176:179], v[108:111]
	v_mfma_f32_16x16x32_bf16 v[104:107], v[156:159], v[176:179], v[104:107]
	v_mfma_f32_16x16x32_bf16 v[92:95], v[148:151], v[184:187], v[92:95]
	v_mfma_f32_16x16x32_bf16 v[88:91], v[156:159], v[184:187], v[88:91]
	v_mfma_f32_16x16x32_bf16 v[76:79], v[148:151], v[192:195], v[76:79]
	v_mfma_f32_16x16x32_bf16 v[72:75], v[156:159], v[192:195], v[72:75]
	s_barrier
	s_add_i32 s26, 0, 0x1c000
	s_add_i32 s27, s28, s97
	v_add_u32_e32 v208, s26, v173
	v_lshl_add_u64 v[212:213], v[212:213], 0, s[22:23]
	s_mov_b32 m0, s27
	ds_read_b128 v[196:199], v208
	ds_read_b128 v[200:203], v208 offset:1024
	ds_read_b128 v[204:207], v208 offset:2048
	ds_read_b128 v[208:211], v208 offset:3072
	global_load_lds_dwordx4 v[212:213], off
	v_lshl_add_u64 v[212:213], v[214:215], 0, s[22:23]
	s_add_i32 m0, s27, 0x2000
	s_nop 0
	global_load_lds_dwordx4 v[212:213], off
	s_barrier
; #define PG8_STAGE(bufoff, gbase, voff) do { _Pragma("unroll") for (int _i = 0; _i < 2; ++_i) \
;     __builtin_amdgcn_global_load_lds((const unsigned*)((const char*)(gbase) + (voff)[_i]), (LAS unsigned*)(lds + (bufoff) + ldsw + _i * 8192), 16, 0, 0); } while (0)
; #define PG8_LDA(dst, b, h) do { _Pragma("unroll") for (int m = 0; m < 4; ++m) _Pragma("unroll") for (int k = 0; k < 2; ++k) dst[m][k] = *(const LAS bf16x8*)(lds + PG8_SA(b, h) + aoff + m * 2048 + k * 1024); } while (0)
; #define PG8_MMA(ai, bj, At, Bt) do { __builtin_amdgcn_s_setprio(1); _Pragma("unroll") for (int m = 0; m < 4; ++m) _Pragma("unroll") for (int n = 0; n < 2; ++n) _Pragma("unroll") for (int k = 0; k < 2; ++k) \
;     acc[ai][bj][m][n] = __builtin_amdgcn_mfma_f32_16x16x32_bf16(Bt[n][k], At[m][k], acc[ai][bj][m][n], 0, 0, 0); __builtin_amdgcn_s_setprio(0); } while (0)
; #define PG8_WAIT_V(n) asm volatile("s_waitcnt vmcnt(" #n ")" ::: "memory")
; #define PG8_WAIT_L(n) asm volatile("s_waitcnt lgkmcnt(" #n ")" ::: "memory")
; #define PG8_BAR __builtin_amdgcn_s_barrier()
; #define PG8_SCHED __builtin_amdgcn_sched_barrier(0)
; template <class Epi>
; __device__ __forceinline__ void gemm_phase(LAS unsigned char* lds, const Gemm g, const Epi& E) {
;     ...
;       PG8_BAR; PG8_WAIT_L(0); PG8_MMA(0, 1, At, B1); PG8_BAR;
;       PG8_LDA(At, 1, 1); PG8_STAGE(PG8_SA(1, 0), a3, voffA);
;       PG8_BAR; PG8_WAIT_L(0); PG8_MMA(1, 0, At, B0); PG8_BAR; PG8_SCHED;
;       PG8_STAGE(PG8_SB(1, 1), b3 + hstepB, voffB);
;       PG8_WAIT_V(6); PG8_BAR; PG8_MMA(1, 1, At, B1); PG8_BAR;
;     ...
;   PG8_WAIT_V(0);
;   if (wr == 0) PG8_BAR;
;   PG8_BAR;
	s_waitcnt lgkmcnt(0)
	s_waitcnt lgkmcnt(0)
	v_mfma_f32_16x16x32_bf16 v[116:119], v[196:199], v[160:163], v[116:119]
	v_mfma_f32_16x16x32_bf16 v[112:115], v[204:207], v[160:163], v[112:115]
	v_mfma_f32_16x16x32_bf16 v[100:103], v[196:199], v[168:171], v[100:103]
	v_mfma_f32_16x16x32_bf16 v[96:99], v[204:207], v[168:171], v[96:99]
	v_mfma_f32_16x16x32_bf16 v[84:87], v[196:199], v[180:183], v[84:87]
	v_mfma_f32_16x16x32_bf16 v[80:83], v[204:207], v[180:183], v[80:83]
	v_mfma_f32_16x16x32_bf16 v[68:71], v[196:199], v[188:191], v[68:71]
	v_mfma_f32_16x16x32_bf16 v[64:67], v[204:207], v[188:191], v[64:67]
	v_mfma_f32_16x16x32_bf16 v[116:119], v[200:203], v[164:167], v[116:119]
	v_mfma_f32_16x16x32_bf16 v[112:115], v[208:211], v[164:167], v[112:115]
	v_mfma_f32_16x16x32_bf16 v[100:103], v[200:203], v[176:179], v[100:103]
	v_mfma_f32_16x16x32_bf16 v[96:99], v[208:211], v[176:179], v[96:99]
	v_mfma_f32_16x16x32_bf16 v[84:87], v[200:203], v[184:187], v[84:87]
	v_mfma_f32_16x16x32_bf16 v[80:83], v[208:211], v[184:187], v[80:83]
	v_mfma_f32_16x16x32_bf16 v[68:71], v[200:203], v[192:195], v[68:71]
	v_mfma_f32_16x16x32_bf16 v[64:67], v[208:211], v[192:195], v[64:67]
	s_mov_b32 m0, s74
	v_lshl_add_u64 v[212:213], v[216:217], 0, s[22:23]
	s_waitcnt vmcnt(10)
	s_barrier
	ds_read_b128 v[160:163], v175 offset:49152
	ds_read_b128 v[164:167], v175 offset:50176
	ds_read_b128 v[168:171], v175 offset:51200
	ds_read_b128 v[176:179], v175 offset:52224
	ds_read_b128 v[180:183], v175 offset:53248
	ds_read_b128 v[184:187], v175 offset:54272
	ds_read_b128 v[188:191], v175 offset:55296
	ds_read_b128 v[192:195], v175 offset:56320
	global_load_lds_dwordx4 v[212:213], off
	v_lshl_add_u64 v[212:213], v[218:219], 0, s[22:23]
	s_mov_b32 m0, s78
	s_nop 0
	global_load_lds_dwordx4 v[212:213], off
	s_barrier
	s_waitcnt lgkmcnt(0)
	s_waitcnt lgkmcnt(0)
	v_mfma_f32_16x16x32_bf16 v[60:63], v[128:131], v[160:163], v[60:63]
	v_mfma_f32_16x16x32_bf16 v[56:59], v[152:155], v[160:163], v[56:59]
	v_mfma_f32_16x16x32_bf16 v[44:47], v[128:131], v[168:171], v[44:47]
	v_mfma_f32_16x16x32_bf16 v[40:43], v[152:155], v[168:171], v[40:43]
	v_mfma_f32_16x16x32_bf16 v[28:31], v[128:131], v[180:183], v[28:31]
	v_mfma_f32_16x16x32_bf16 v[24:27], v[152:155], v[180:183], v[24:27]
	v_mfma_f32_16x16x32_bf16 v[12:15], v[128:131], v[188:191], v[12:15]
	v_mfma_f32_16x16x32_bf16 v[8:11], v[152:155], v[188:191], v[8:11]
	v_mfma_f32_16x16x32_bf16 v[60:63], v[148:151], v[164:167], v[60:63]
	v_mfma_f32_16x16x32_bf16 v[56:59], v[156:159], v[164:167], v[56:59]
	v_mfma_f32_16x16x32_bf16 v[44:47], v[148:151], v[176:179], v[44:47]
	v_mfma_f32_16x16x32_bf16 v[40:43], v[156:159], v[176:179], v[40:43]
	v_mfma_f32_16x16x32_bf16 v[28:31], v[148:151], v[184:187], v[28:31]
	v_mfma_f32_16x16x32_bf16 v[24:27], v[156:159], v[184:187], v[24:27]
	v_mfma_f32_16x16x32_bf16 v[12:15], v[148:151], v[192:195], v[12:15]
	v_mfma_f32_16x16x32_bf16 v[8:11], v[156:159], v[192:195], v[8:11]
	s_barrier
	s_add_i32 s26, s26, s97
	v_lshl_add_u64 v[128:129], v[220:221], 0, s[22:23]
	s_mov_b32 m0, s26
	s_nop 0
	global_load_lds_dwordx4 v[128:129], off
	v_lshl_add_u64 v[128:129], v[222:223], 0, s[22:23]
	s_add_i32 m0, s26, 0x2000
	s_nop 0
	global_load_lds_dwordx4 v[128:129], off
	s_waitcnt vmcnt(6)
	s_barrier
	v_mfma_f32_16x16x32_bf16 v[52:55], v[196:199], v[160:163], v[52:55]
	v_mfma_f32_16x16x32_bf16 v[48:51], v[204:207], v[160:163], v[48:51]
	v_mfma_f32_16x16x32_bf16 v[36:39], v[196:199], v[168:171], v[36:39]
	v_mfma_f32_16x16x32_bf16 v[32:35], v[204:207], v[168:171], v[32:35]
	v_mfma_f32_16x16x32_bf16 v[20:23], v[196:199], v[180:183], v[20:23]
	v_mfma_f32_16x16x32_bf16 v[16:19], v[204:207], v[180:183], v[16:19]
	v_mfma_f32_16x16x32_bf16 v[4:7], v[196:199], v[188:191], v[4:7]
	v_mfma_f32_16x16x32_bf16 v[0:3], v[204:207], v[188:191], v[0:3]
	v_mfma_f32_16x16x32_bf16 v[52:55], v[200:203], v[164:167], v[52:55]
	v_mfma_f32_16x16x32_bf16 v[48:51], v[208:211], v[164:167], v[48:51]
	v_mfma_f32_16x16x32_bf16 v[36:39], v[200:203], v[176:179], v[36:39]
	v_mfma_f32_16x16x32_bf16 v[32:35], v[208:211], v[176:179], v[32:35]
	v_mfma_f32_16x16x32_bf16 v[20:23], v[200:203], v[184:187], v[20:23]
	v_mfma_f32_16x16x32_bf16 v[16:19], v[208:211], v[184:187], v[16:19]
	v_mfma_f32_16x16x32_bf16 v[4:7], v[200:203], v[192:195], v[4:7]
	v_mfma_f32_16x16x32_bf16 v[0:3], v[208:211], v[192:195], v[0:3]
	s_add_u32 s2, s2, 0x100
	s_addc_u32 s3, s3, 0
	s_add_u32 s38, s38, 0x100
	s_addc_u32 s39, s39, 0
	s_cmp_ge_u32 s76, s72
	s_mov_b32 s26, s76
	s_barrier
	s_cbranch_scc0 .LBB0_579
	s_branch .Lgemm_exit
.LBB0_1252:
	s_setprio 0
	s_waitcnt vmcnt(0)
	v_readlane_b32 s0, v255, 29
	s_cmpk_gt_u32 s0, 0xff
	s_cbranch_scc1 .LBB0_1254
	s_barrier
